# barrier poll loops without s_sleep between polls
# speedup vs baseline: 1.0006x; 1.0003x over previous
.Lp0_spin:
	global_load_dword v3, v1, s[8:9] sc1
	s_waitcnt vmcnt(0) lgkmcnt(0)
	v_cmp_ge_u32_e32 vcc, v3, v2
	s_cbranch_vccnz .Lp0_spin_done
	s_nop 0
	s_add_u32 s10, s10, 1
	s_cmp_lt_u32 s10, 0x100000
	s_cbranch_scc1 .Lp0_spin

.Llb182_spin:
	global_load_dword v2, v1, s[10:11] sc1
	s_waitcnt vmcnt(0)
	v_cmp_ge_u32_e32 vcc, v2, v17
	s_cbranch_vccnz .Llb182_done
	s_nop 0
	s_add_u32 s9, s9, 1
	s_cmp_lt_u32 s9, 0x100000
	s_cbranch_scc1 .Llb182_spin

.Lp3_spin:
	global_load_dword v2, v1, s[10:11] sc1
	s_waitcnt vmcnt(0) lgkmcnt(0)
	v_cmp_ge_u32_e32 vcc, v2, v17
	s_cbranch_vccnz .Lp3_spin_done
	s_nop 0
	s_add_u32 s8, s8, 1
	s_cmp_lt_u32 s8, 0x100000
	s_cbranch_scc1 .Lp3_spin

.Llb487_spin:
	global_load_dword v2, v1, s[8:9] sc1
	s_waitcnt vmcnt(0)
	v_cmp_ge_u32_e32 vcc, v2, v17
	s_cbranch_vccnz .Llb487_done
	s_nop 0
	s_add_u32 s6, s6, 1
	s_cmp_lt_u32 s6, 0x100000
	s_cbranch_scc1 .Llb487_spin

.Llb577_spin:
	global_load_dword v2, v1, s[10:11] sc1
	s_waitcnt vmcnt(0)
	v_cmp_ge_u32_e32 vcc, v2, v17
	s_cbranch_vccnz .Llb577_done
	s_nop 0
	s_add_u32 s8, s8, 1
	s_cmp_lt_u32 s8, 0x100000
	s_cbranch_scc1 .Llb577_spin

.Lr3_spin:
	global_load_dword v3, v1, s[6:7] sc1
	s_waitcnt vmcnt(0) lgkmcnt(0)
	v_cmp_ge_u32_e32 vcc, v3, v2
	s_cbranch_vccnz .Lr3_spin_done
	s_nop 0
	s_add_u32 s8, s8, 1
	s_cmp_lt_u32 s8, 0x100000
	s_cbranch_scc1 .Lr3_spin

.Llb715_spin:
	global_load_dword v17, v4, s[12:13] sc1
	s_waitcnt vmcnt(0)
	v_cmp_ge_u32_e32 vcc, v17, v3
	s_cbranch_vccnz .Llb715_done
	s_nop 0
	s_add_u32 s16, s16, 1
	s_cmp_lt_u32 s16, 0x100000
	s_cbranch_scc1 .Llb715_spin

.Lff1b_spin:
	global_load_dword v170, v168, s[46:47] sc1
	s_waitcnt vmcnt(0) lgkmcnt(0)
	v_cmp_ge_u32_e32 vcc, v170, v169
	s_cbranch_vccnz .Lff1b_wait_join
	s_nop 0
	s_add_u32 s26, s26, 1
	s_cmp_lt_u32 s26, 0x100000
	s_cbranch_scc1 .Lff1b_spin

.Llb865_spin:
	global_load_dword v17, v4, s[12:13] sc1
	s_waitcnt vmcnt(0) lgkmcnt(0)
	v_cmp_ge_u32_e32 vcc, v17, v3
	s_cbranch_vccnz .Llb865_join
	s_nop 0
	s_add_u32 s16, s16, 1
	s_cmp_lt_u32 s16, 0x100000
	s_cbranch_scc1 .Llb865_spin

.Lr4_spin:
	global_load_dword v4, v2, s[26:27] sc1
	s_waitcnt vmcnt(0) lgkmcnt(0)
	v_cmp_ge_u32_e32 vcc, v4, v3
	s_cbranch_vccnz .Lr4_spin_done
	s_nop 0
	s_add_u32 s28, s28, 1
	s_cmp_lt_u32 s28, 0x100000
	s_cbranch_scc1 .Lr4_spin
